# P2 work queue: next item index fetched during the current item's epilogue (after diff TAIL barrier / last dilated merge)
# speedup vs baseline: 1.1809x; 1.1809x over previous
.LBB0_246:
	s_and_saveexec_b64 s[4:5], s[0:1]
	s_cbranch_execz .LBB0_250
	s_waitcnt vmcnt(0)
	v_mov_b32_e32 v0, v242
	v_mov_b32_e32 v1, s63
	s_nop 0
	ds_write_b32 v1, v0

.LBB0_263:
	v_exp_f32_e32 v80, v80
	v_exp_f32_e32 v81, v81
	v_exp_f32_e32 v82, v82
	v_exp_f32_e32 v83, v83
	v_add_f32_e32 v96, 0, v80
	v_exp_f32_e32 v84, v84
	v_add_f32_e32 v96, v81, v96
	v_exp_f32_e32 v85, v85
	v_add_f32_e32 v96, v82, v96
	v_exp_f32_e32 v86, v86
	v_add_f32_e32 v96, v83, v96
	v_exp_f32_e32 v87, v87
	v_add_f32_e32 v96, v84, v96
	v_exp_f32_e32 v88, v88
	v_add_f32_e32 v96, v85, v96
	v_exp_f32_e32 v89, v89
	v_add_f32_e32 v96, v86, v96
	v_exp_f32_e32 v90, v90
	v_add_f32_e32 v96, v87, v96
	v_exp_f32_e32 v91, v91
	v_add_f32_e32 v96, v88, v96
	v_exp_f32_e32 v92, v92
	v_add_f32_e32 v96, v89, v96
	v_exp_f32_e32 v93, v93
	v_add_f32_e32 v96, v90, v96
	v_exp_f32_e32 v94, v94
	v_add_f32_e32 v96, v91, v96
	v_exp_f32_e32 v95, v95
	v_add_f32_e32 v96, v92, v96
	v_add_f32_e32 v96, v93, v96
	v_add_f32_e32 v96, v94, v96
	v_cvt_pk_bf16_f32 v80, v80, v81
	v_cvt_pk_bf16_f32 v81, v82, v83
	v_cvt_pk_bf16_f32 v82, v84, v85
	v_cvt_pk_bf16_f32 v84, v88, v89
	v_exp_f32_e32 v88, v64
	v_exp_f32_e32 v89, v65
	v_exp_f32_e32 v101, v76
	v_exp_f32_e32 v102, v77
	v_add_f32_e32 v96, v95, v96
	v_cvt_pk_bf16_f32 v83, v86, v87
	v_cvt_pk_bf16_f32 v85, v90, v91
	v_cvt_pk_bf16_f32 v86, v92, v93
	v_cvt_pk_bf16_f32 v87, v94, v95
	v_exp_f32_e32 v90, v66
	v_exp_f32_e32 v91, v67
	v_exp_f32_e32 v92, v68
	v_exp_f32_e32 v93, v69
	v_exp_f32_e32 v94, v70
	v_exp_f32_e32 v95, v71
	v_exp_f32_e32 v97, v72
	v_exp_f32_e32 v98, v73
	v_exp_f32_e32 v99, v74
	v_exp_f32_e32 v100, v75
	v_exp_f32_e32 v103, v78
	v_exp_f32_e32 v104, v79
	s_not_b32 s4, s70
	s_lshl_b32 s4, s4, 15
	s_and_b32 s4, s4, 0x8000
	v_cvt_pk_bf16_f32 v64, v88, v89
	v_cvt_pk_bf16_f32 v70, v101, v102
	v_cvt_pk_bf16_f32 v65, v90, v91
	v_cvt_pk_bf16_f32 v66, v92, v93
	v_cvt_pk_bf16_f32 v67, v94, v95
	v_cvt_pk_bf16_f32 v68, v97, v98
	v_cvt_pk_bf16_f32 v69, v99, v100
	v_cvt_pk_bf16_f32 v71, v103, v104
	s_add_i32 s4, s4, 0
	v_add_u32_e32 v105, s4, v165
	v_add_u32_e32 v107, s4, v167
	v_add_u32_e32 v106, s4, v166
	ds_read_b64_tr_b16 v[72:73], v105 offset:16384
	ds_read_b64_tr_b16 v[74:75], v106 offset:16384
	v_add_u32_e32 v108, s4, v168
	ds_read_b64_tr_b16 v[76:77], v107 offset:16384
	ds_read_b64_tr_b16 v[78:79], v108 offset:16384
	v_add_u32_e32 v109, s4, v161
	v_add_u32_e32 v111, s4, v163
	s_waitcnt lgkmcnt(2)
	v_mfma_f32_32x32x16_bf16 v[48:63], v[72:75], v[80:83], v[48:63]
	v_add_u32_e32 v110, s4, v162
	ds_read_b64_tr_b16 v[72:73], v109 offset:16384
	ds_read_b64_tr_b16 v[74:75], v110 offset:16384
	v_add_u32_e32 v112, s4, v164
	s_waitcnt lgkmcnt(2)
	v_mfma_f32_32x32x16_bf16 v[32:47], v[76:79], v[80:83], v[32:47]
	ds_read_b64_tr_b16 v[76:77], v111 offset:16384
	ds_read_b64_tr_b16 v[78:79], v112 offset:16384
	s_waitcnt lgkmcnt(2)
	v_mfma_f32_32x32x16_bf16 v[16:31], v[72:75], v[80:83], v[16:31]
	s_waitcnt lgkmcnt(0)
	v_mfma_f32_32x32x16_bf16 v[0:15], v[76:79], v[80:83], v[0:15]
	ds_read_b64_tr_b16 v[72:73], v105 offset:20480
	ds_read_b64_tr_b16 v[74:75], v106 offset:20480
	ds_read_b64_tr_b16 v[76:77], v107 offset:20480
	ds_read_b64_tr_b16 v[78:79], v108 offset:20480
	s_waitcnt lgkmcnt(2)
	v_mfma_f32_32x32x16_bf16 v[48:63], v[72:75], v[84:87], v[48:63]
	s_waitcnt lgkmcnt(0)
	v_mfma_f32_32x32x16_bf16 v[32:47], v[76:79], v[84:87], v[32:47]
	ds_read_b64_tr_b16 v[72:73], v109 offset:20480
	ds_read_b64_tr_b16 v[74:75], v110 offset:20480
	ds_read_b64_tr_b16 v[76:77], v111 offset:20480
	ds_read_b64_tr_b16 v[78:79], v112 offset:20480
	s_waitcnt lgkmcnt(2)
	v_mfma_f32_32x32x16_bf16 v[16:31], v[72:75], v[84:87], v[16:31]
	s_waitcnt lgkmcnt(0)
	v_mfma_f32_32x32x16_bf16 v[0:15], v[76:79], v[84:87], v[0:15]
	ds_read_b64_tr_b16 v[72:73], v105 offset:24576
	ds_read_b64_tr_b16 v[74:75], v106 offset:24576
	ds_read_b64_tr_b16 v[76:77], v107 offset:24576
	ds_read_b64_tr_b16 v[78:79], v108 offset:24576
	s_waitcnt lgkmcnt(2)
	v_mfma_f32_32x32x16_bf16 v[48:63], v[72:75], v[64:67], v[48:63]
	s_waitcnt lgkmcnt(0)
	v_mfma_f32_32x32x16_bf16 v[32:47], v[76:79], v[64:67], v[32:47]
	ds_read_b64_tr_b16 v[72:73], v109 offset:24576
	ds_read_b64_tr_b16 v[74:75], v110 offset:24576
	ds_read_b64_tr_b16 v[76:77], v111 offset:24576
	ds_read_b64_tr_b16 v[78:79], v112 offset:24576
	s_waitcnt lgkmcnt(2)
	v_mfma_f32_32x32x16_bf16 v[16:31], v[72:75], v[64:67], v[16:31]
	s_waitcnt lgkmcnt(0)
	v_mfma_f32_32x32x16_bf16 v[0:15], v[76:79], v[64:67], v[0:15]
	ds_read_b64_tr_b16 v[64:65], v105 offset:28672
	ds_read_b64_tr_b16 v[66:67], v106 offset:28672
	ds_read_b64_tr_b16 v[72:73], v107 offset:28672
	ds_read_b64_tr_b16 v[74:75], v108 offset:28672
	s_waitcnt lgkmcnt(2)
	v_mfma_f32_32x32x16_bf16 v[48:63], v[64:67], v[68:71], v[48:63]
	s_waitcnt lgkmcnt(0)
	v_mfma_f32_32x32x16_bf16 v[32:47], v[72:75], v[68:71], v[32:47]
	ds_read_b64_tr_b16 v[64:65], v109 offset:28672
	ds_read_b64_tr_b16 v[66:67], v110 offset:28672
	ds_read_b64_tr_b16 v[72:73], v111 offset:28672
	ds_read_b64_tr_b16 v[74:75], v112 offset:28672
	s_waitcnt lgkmcnt(2)
	v_mfma_f32_32x32x16_bf16 v[16:31], v[64:67], v[68:71], v[16:31]
	s_waitcnt lgkmcnt(0)
	v_mfma_f32_32x32x16_bf16 v[0:15], v[72:75], v[68:71], v[0:15]
	v_add_f32_e32 v64, v88, v96
	v_add_f32_e32 v64, v89, v64
	v_add_f32_e32 v64, v90, v64
	v_add_f32_e32 v64, v91, v64
	v_add_f32_e32 v64, v92, v64
	v_add_f32_e32 v64, v93, v64
	v_add_f32_e32 v64, v94, v64
	v_add_f32_e32 v64, v95, v64
	v_add_f32_e32 v64, v97, v64
	v_add_f32_e32 v64, v98, v64
	v_add_f32_e32 v64, v99, v64
	v_add_f32_e32 v64, v100, v64
	v_add_f32_e32 v64, v101, v64
	v_add_f32_e32 v64, v102, v64
	v_add_f32_e32 v64, v103, v64
	v_add_f32_e32 v64, v104, v64
	v_add_f32_e32 v64, v188, v64
	ds_bpermute_b32 v65, v194, v64
	s_lshl_b32 s6, s69, 14
	s_waitcnt vmcnt(0) lgkmcnt(0)
	s_barrier
	s_and_saveexec_b64 s[98:99], s[0:1]
	s_cbranch_execz .Lqpf_x3
	v_mov_b32_e32 v243, 1
	global_atomic_add v242, v131, v243, s[52:53] sc0
.Lqpf_x3:
	s_or_b64 exec, exec, s[98:99]
	s_waitcnt lgkmcnt(0)
	v_add_f32_e32 v64, v64, v65
	v_div_scale_f32 v65, s[4:5], v64, v64, 1.0
	v_rcp_f32_e32 v66, v65
	v_div_scale_f32 v67, vcc, 1.0, v64, 1.0
	s_add_i32 s4, s6, 0
	v_fma_f32 v68, -v65, v66, 1.0
	v_fmac_f32_e32 v66, v68, v66
	v_mul_f32_e32 v68, v67, v66
	v_fma_f32 v69, -v65, v68, v67
	v_fmac_f32_e32 v68, v69, v66
	v_fma_f32 v65, -v65, v68, v67
	v_div_fmas_f32 v65, v65, v66, v68
	s_add_i32 s4, s4, 0x10000
	v_div_fixup_f32 v70, v65, v64, 1.0
	s_cmp_lg_u32 s37, 1
	v_lshl_add_u32 v64, v157, 2, s4
	s_cbranch_scc1 .LBB0_265
	v_mul_f32_e32 v65, v48, v70
	v_mul_f32_e32 v66, v49, v70
	ds_write2st64_b32 v64, v65, v66 offset1:1
	v_mul_f32_e32 v65, v50, v70
	v_mul_f32_e32 v66, v51, v70
	ds_write2st64_b32 v64, v65, v66 offset0:2 offset1:3
	v_mul_f32_e32 v65, v52, v70
	v_mul_f32_e32 v66, v53, v70
	ds_write2st64_b32 v64, v65, v66 offset0:4 offset1:5
	v_mul_f32_e32 v65, v54, v70
	v_mul_f32_e32 v66, v55, v70
	ds_write2st64_b32 v64, v65, v66 offset0:6 offset1:7
	v_mul_f32_e32 v65, v56, v70
	v_mul_f32_e32 v66, v57, v70
	ds_write2st64_b32 v64, v65, v66 offset0:8 offset1:9
	v_mul_f32_e32 v65, v58, v70
	v_mul_f32_e32 v66, v59, v70
	ds_write2st64_b32 v64, v65, v66 offset0:10 offset1:11
	v_mul_f32_e32 v65, v60, v70
	v_mul_f32_e32 v66, v61, v70
	ds_write2st64_b32 v64, v65, v66 offset0:12 offset1:13
	v_mul_f32_e32 v65, v62, v70
	v_mul_f32_e32 v66, v63, v70
	ds_write2st64_b32 v64, v65, v66 offset0:14 offset1:15
	v_mul_f32_e32 v65, v32, v70
	v_mul_f32_e32 v66, v33, v70
	ds_write2st64_b32 v64, v65, v66 offset0:16 offset1:17
	v_mul_f32_e32 v65, v34, v70
	v_mul_f32_e32 v66, v35, v70
	ds_write2st64_b32 v64, v65, v66 offset0:18 offset1:19
	v_mul_f32_e32 v65, v36, v70
	v_mul_f32_e32 v66, v37, v70
	ds_write2st64_b32 v64, v65, v66 offset0:20 offset1:21
	v_mul_f32_e32 v65, v38, v70
	v_mul_f32_e32 v66, v39, v70
	ds_write2st64_b32 v64, v65, v66 offset0:22 offset1:23
	v_mul_f32_e32 v65, v40, v70
	v_mul_f32_e32 v66, v41, v70
	ds_write2st64_b32 v64, v65, v66 offset0:24 offset1:25
	v_mul_f32_e32 v65, v42, v70
	v_mul_f32_e32 v66, v43, v70
	ds_write2st64_b32 v64, v65, v66 offset0:26 offset1:27
	v_mul_f32_e32 v65, v44, v70
	v_mul_f32_e32 v66, v45, v70
	ds_write2st64_b32 v64, v65, v66 offset0:28 offset1:29
	v_mul_f32_e32 v65, v46, v70
	v_mul_f32_e32 v66, v47, v70
	ds_write2st64_b32 v64, v65, v66 offset0:30 offset1:31
	v_mul_f32_e32 v65, v16, v70
	v_mul_f32_e32 v66, v17, v70
	ds_write2st64_b32 v64, v65, v66 offset0:32 offset1:33
	v_mul_f32_e32 v65, v18, v70
	v_mul_f32_e32 v66, v19, v70
	ds_write2st64_b32 v64, v65, v66 offset0:34 offset1:35
	v_mul_f32_e32 v65, v20, v70
	v_mul_f32_e32 v66, v21, v70
	ds_write2st64_b32 v64, v65, v66 offset0:36 offset1:37
	v_mul_f32_e32 v65, v22, v70
	v_mul_f32_e32 v66, v23, v70
	ds_write2st64_b32 v64, v65, v66 offset0:38 offset1:39
	v_mul_f32_e32 v65, v24, v70
	v_mul_f32_e32 v66, v25, v70
	ds_write2st64_b32 v64, v65, v66 offset0:40 offset1:41
	v_mul_f32_e32 v65, v26, v70
	v_mul_f32_e32 v66, v27, v70
	ds_write2st64_b32 v64, v65, v66 offset0:42 offset1:43
	v_mul_f32_e32 v65, v28, v70
	v_mul_f32_e32 v66, v29, v70
	ds_write2st64_b32 v64, v65, v66 offset0:44 offset1:45
	v_mul_f32_e32 v65, v30, v70
	v_mul_f32_e32 v66, v31, v70
	ds_write2st64_b32 v64, v65, v66 offset0:46 offset1:47
	v_mul_f32_e32 v65, v0, v70
	v_mul_f32_e32 v66, v1, v70
	ds_write2st64_b32 v64, v65, v66 offset0:48 offset1:49
	v_mul_f32_e32 v65, v2, v70
	v_mul_f32_e32 v66, v3, v70
	ds_write2st64_b32 v64, v65, v66 offset0:50 offset1:51
	v_mul_f32_e32 v65, v4, v70
	v_mul_f32_e32 v66, v5, v70
	ds_write2st64_b32 v64, v65, v66 offset0:52 offset1:53
	v_mul_f32_e32 v65, v6, v70
	v_mul_f32_e32 v66, v7, v70
	ds_write2st64_b32 v64, v65, v66 offset0:54 offset1:55
	v_mul_f32_e32 v65, v8, v70
	v_mul_f32_e32 v66, v9, v70
	ds_write2st64_b32 v64, v65, v66 offset0:56 offset1:57
	v_mul_f32_e32 v65, v10, v70
	v_mul_f32_e32 v66, v11, v70
	ds_write2st64_b32 v64, v65, v66 offset0:58 offset1:59
	v_mul_f32_e32 v65, v12, v70
	v_mul_f32_e32 v66, v13, v70
	ds_write2st64_b32 v64, v65, v66 offset0:60 offset1:61
	v_mul_f32_e32 v65, v14, v70
	v_mul_f32_e32 v66, v15, v70
	ds_write2st64_b32 v64, v65, v66 offset0:62 offset1:63

.LBB0_279:
	s_cmp_lg_u32 s75, 3
	s_cbranch_scc1 .Lqpf_skip2
	s_and_saveexec_b64 s[98:99], s[0:1]
	s_cbranch_execz .Lqpf_x2
	v_mov_b32_e32 v243, 1
	global_atomic_add v242, v131, v243, s[52:53] sc0
.Lqpf_x2:
	s_or_b64 exec, exec, s[98:99]

.LBB0_307:
	v_exp_f32_e32 v80, v80
	v_exp_f32_e32 v81, v81
	v_exp_f32_e32 v82, v82
	v_exp_f32_e32 v83, v83
	v_add_f32_e32 v96, 0, v80
	v_exp_f32_e32 v84, v84
	v_add_f32_e32 v96, v81, v96
	v_exp_f32_e32 v85, v85
	v_add_f32_e32 v96, v82, v96
	v_exp_f32_e32 v86, v86
	v_add_f32_e32 v96, v83, v96
	v_exp_f32_e32 v87, v87
	v_add_f32_e32 v96, v84, v96
	v_exp_f32_e32 v88, v88
	v_add_f32_e32 v96, v85, v96
	v_exp_f32_e32 v89, v89
	v_add_f32_e32 v96, v86, v96
	v_exp_f32_e32 v90, v90
	v_add_f32_e32 v96, v87, v96
	v_exp_f32_e32 v91, v91
	v_add_f32_e32 v96, v88, v96
	v_exp_f32_e32 v92, v92
	v_add_f32_e32 v96, v89, v96
	v_exp_f32_e32 v93, v93
	v_add_f32_e32 v96, v90, v96
	v_exp_f32_e32 v94, v94
	v_add_f32_e32 v96, v91, v96
	v_exp_f32_e32 v95, v95
	v_add_f32_e32 v96, v92, v96
	v_add_f32_e32 v96, v93, v96
	v_add_f32_e32 v96, v94, v96
	v_cvt_pk_bf16_f32 v80, v80, v81
	v_cvt_pk_bf16_f32 v81, v82, v83
	v_cvt_pk_bf16_f32 v82, v84, v85
	v_cvt_pk_bf16_f32 v84, v88, v89
	v_exp_f32_e32 v88, v64
	v_exp_f32_e32 v89, v65
	v_exp_f32_e32 v101, v76
	v_exp_f32_e32 v102, v77
	v_add_f32_e32 v96, v95, v96
	v_cvt_pk_bf16_f32 v83, v86, v87
	v_cvt_pk_bf16_f32 v85, v90, v91
	v_cvt_pk_bf16_f32 v86, v92, v93
	v_cvt_pk_bf16_f32 v87, v94, v95
	v_exp_f32_e32 v90, v66
	v_exp_f32_e32 v91, v67
	v_exp_f32_e32 v92, v68
	v_exp_f32_e32 v93, v69
	v_exp_f32_e32 v94, v70
	v_exp_f32_e32 v95, v71
	v_exp_f32_e32 v97, v72
	v_exp_f32_e32 v98, v73
	v_exp_f32_e32 v99, v74
	v_exp_f32_e32 v100, v75
	v_exp_f32_e32 v103, v78
	v_exp_f32_e32 v104, v79
	s_not_b32 s4, s20
	s_lshl_b32 s4, s4, 15
	s_and_b32 s4, s4, 0x8000
	v_cvt_pk_bf16_f32 v64, v88, v89
	v_cvt_pk_bf16_f32 v70, v101, v102
	v_cvt_pk_bf16_f32 v65, v90, v91
	v_cvt_pk_bf16_f32 v66, v92, v93
	v_cvt_pk_bf16_f32 v67, v94, v95
	v_cvt_pk_bf16_f32 v68, v97, v98
	v_cvt_pk_bf16_f32 v69, v99, v100
	v_cvt_pk_bf16_f32 v71, v103, v104
	s_add_i32 s4, s4, 0
	v_add_u32_e32 v105, s4, v165
	v_add_u32_e32 v107, s4, v167
	v_add_u32_e32 v106, s4, v166
	ds_read_b64_tr_b16 v[72:73], v105 offset:16384
	ds_read_b64_tr_b16 v[74:75], v106 offset:16384
	v_add_u32_e32 v108, s4, v168
	ds_read_b64_tr_b16 v[76:77], v107 offset:16384
	ds_read_b64_tr_b16 v[78:79], v108 offset:16384
	v_add_u32_e32 v109, s4, v161
	v_add_u32_e32 v111, s4, v163
	s_waitcnt lgkmcnt(2)
	v_mfma_f32_32x32x16_bf16 v[48:63], v[72:75], v[80:83], v[48:63]
	v_add_u32_e32 v110, s4, v162
	ds_read_b64_tr_b16 v[72:73], v109 offset:16384
	ds_read_b64_tr_b16 v[74:75], v110 offset:16384
	v_add_u32_e32 v112, s4, v164
	s_waitcnt lgkmcnt(2)
	v_mfma_f32_32x32x16_bf16 v[32:47], v[76:79], v[80:83], v[32:47]
	ds_read_b64_tr_b16 v[76:77], v111 offset:16384
	ds_read_b64_tr_b16 v[78:79], v112 offset:16384
	s_waitcnt lgkmcnt(2)
	v_mfma_f32_32x32x16_bf16 v[16:31], v[72:75], v[80:83], v[16:31]
	s_waitcnt lgkmcnt(0)
	v_mfma_f32_32x32x16_bf16 v[0:15], v[76:79], v[80:83], v[0:15]
	ds_read_b64_tr_b16 v[72:73], v105 offset:20480
	ds_read_b64_tr_b16 v[74:75], v106 offset:20480
	ds_read_b64_tr_b16 v[76:77], v107 offset:20480
	ds_read_b64_tr_b16 v[78:79], v108 offset:20480
	s_waitcnt lgkmcnt(2)
	v_mfma_f32_32x32x16_bf16 v[48:63], v[72:75], v[84:87], v[48:63]
	s_waitcnt lgkmcnt(0)
	v_mfma_f32_32x32x16_bf16 v[32:47], v[76:79], v[84:87], v[32:47]
	ds_read_b64_tr_b16 v[72:73], v109 offset:20480
	ds_read_b64_tr_b16 v[74:75], v110 offset:20480
	ds_read_b64_tr_b16 v[76:77], v111 offset:20480
	ds_read_b64_tr_b16 v[78:79], v112 offset:20480
	s_waitcnt lgkmcnt(2)
	v_mfma_f32_32x32x16_bf16 v[16:31], v[72:75], v[84:87], v[16:31]
	s_waitcnt lgkmcnt(0)
	v_mfma_f32_32x32x16_bf16 v[0:15], v[76:79], v[84:87], v[0:15]
	ds_read_b64_tr_b16 v[72:73], v105 offset:24576
	ds_read_b64_tr_b16 v[74:75], v106 offset:24576
	ds_read_b64_tr_b16 v[76:77], v107 offset:24576
	ds_read_b64_tr_b16 v[78:79], v108 offset:24576
	s_waitcnt lgkmcnt(2)
	v_mfma_f32_32x32x16_bf16 v[48:63], v[72:75], v[64:67], v[48:63]
	s_waitcnt lgkmcnt(0)
	v_mfma_f32_32x32x16_bf16 v[32:47], v[76:79], v[64:67], v[32:47]
	ds_read_b64_tr_b16 v[72:73], v109 offset:24576
	ds_read_b64_tr_b16 v[74:75], v110 offset:24576
	ds_read_b64_tr_b16 v[76:77], v111 offset:24576
	ds_read_b64_tr_b16 v[78:79], v112 offset:24576
	s_waitcnt lgkmcnt(2)
	v_mfma_f32_32x32x16_bf16 v[16:31], v[72:75], v[64:67], v[16:31]
	s_waitcnt lgkmcnt(0)
	v_mfma_f32_32x32x16_bf16 v[0:15], v[76:79], v[64:67], v[0:15]
	ds_read_b64_tr_b16 v[64:65], v105 offset:28672
	ds_read_b64_tr_b16 v[66:67], v106 offset:28672
	ds_read_b64_tr_b16 v[72:73], v107 offset:28672
	ds_read_b64_tr_b16 v[74:75], v108 offset:28672
	s_waitcnt lgkmcnt(2)
	v_mfma_f32_32x32x16_bf16 v[48:63], v[64:67], v[68:71], v[48:63]
	s_waitcnt lgkmcnt(0)
	v_mfma_f32_32x32x16_bf16 v[32:47], v[72:75], v[68:71], v[32:47]
	ds_read_b64_tr_b16 v[64:65], v109 offset:28672
	ds_read_b64_tr_b16 v[66:67], v110 offset:28672
	ds_read_b64_tr_b16 v[72:73], v111 offset:28672
	ds_read_b64_tr_b16 v[74:75], v112 offset:28672
	s_waitcnt lgkmcnt(2)
	v_mfma_f32_32x32x16_bf16 v[16:31], v[64:67], v[68:71], v[16:31]
	s_waitcnt lgkmcnt(0)
	v_mfma_f32_32x32x16_bf16 v[0:15], v[72:75], v[68:71], v[0:15]
	v_add_f32_e32 v64, v88, v96
	v_add_f32_e32 v64, v89, v64
	v_add_f32_e32 v64, v90, v64
	v_add_f32_e32 v64, v91, v64
	v_add_f32_e32 v64, v92, v64
	v_add_f32_e32 v64, v93, v64
	v_add_f32_e32 v64, v94, v64
	v_add_f32_e32 v64, v95, v64
	v_add_f32_e32 v64, v97, v64
	v_add_f32_e32 v64, v98, v64
	v_add_f32_e32 v64, v99, v64
	v_add_f32_e32 v64, v100, v64
	v_add_f32_e32 v64, v101, v64
	v_add_f32_e32 v64, v102, v64
	v_add_f32_e32 v64, v103, v64
	v_add_f32_e32 v64, v104, v64
	v_add_f32_e32 v64, v188, v64
	ds_bpermute_b32 v65, v194, v64
	s_lshl_b32 s6, s69, 14
	s_waitcnt vmcnt(0) lgkmcnt(0)
	s_barrier
	s_and_saveexec_b64 s[98:99], s[0:1]
	s_cbranch_execz .Lqpf_x1
	v_mov_b32_e32 v243, 1
	global_atomic_add v242, v131, v243, s[52:53] sc0
